# v14 stack + accumulator zero-init for the (never taken) K<64 path moved out of line
# baseline (speedup 1.0000x reference)
.Lzinit_0:
	v_mov_b32_e32 v115, 0
	v_mov_b32_e32 v114, v115
	v_mov_b32_e32 v113, v115
	v_mov_b32_e32 v112, v115
	v_mov_b32_e32 v123, v115
	v_mov_b32_e32 v122, v115
	v_mov_b32_e32 v121, v115
	v_mov_b32_e32 v120, v115
	v_mov_b32_e32 v99, v115
	v_mov_b32_e32 v98, v115
	v_mov_b32_e32 v97, v115
	v_mov_b32_e32 v96, v115
	v_mov_b32_e32 v107, v115
	v_mov_b32_e32 v106, v115
	v_mov_b32_e32 v105, v115
	v_mov_b32_e32 v104, v115
	v_mov_b32_e32 v83, v115
	v_mov_b32_e32 v82, v115
	v_mov_b32_e32 v81, v115
	v_mov_b32_e32 v80, v115
	v_mov_b32_e32 v91, v115
	v_mov_b32_e32 v90, v115
	v_mov_b32_e32 v89, v115
	v_mov_b32_e32 v88, v115
	v_mov_b32_e32 v67, v115
	v_mov_b32_e32 v66, v115
	v_mov_b32_e32 v65, v115
	v_mov_b32_e32 v64, v115
	v_mov_b32_e32 v75, v115
	v_mov_b32_e32 v74, v115
	v_mov_b32_e32 v73, v115
	v_mov_b32_e32 v72, v115
	v_mov_b32_e32 v119, v115
	v_mov_b32_e32 v118, v115
	v_mov_b32_e32 v117, v115
	v_mov_b32_e32 v116, v115
	v_mov_b32_e32 v127, v115
	v_mov_b32_e32 v126, v115
	v_mov_b32_e32 v125, v115
	v_mov_b32_e32 v124, v115
	v_mov_b32_e32 v103, v115
	v_mov_b32_e32 v102, v115
	v_mov_b32_e32 v101, v115
	v_mov_b32_e32 v100, v115
	v_mov_b32_e32 v111, v115
	v_mov_b32_e32 v110, v115
	v_mov_b32_e32 v109, v115
	v_mov_b32_e32 v108, v115
	v_mov_b32_e32 v87, v115
	v_mov_b32_e32 v86, v115
	v_mov_b32_e32 v85, v115
	v_mov_b32_e32 v84, v115
	v_mov_b32_e32 v95, v115
	v_mov_b32_e32 v94, v115
	v_mov_b32_e32 v93, v115
	v_mov_b32_e32 v92, v115
	v_mov_b32_e32 v71, v115
	v_mov_b32_e32 v70, v115
	v_mov_b32_e32 v69, v115
	v_mov_b32_e32 v68, v115
	v_mov_b32_e32 v79, v115
	v_mov_b32_e32 v78, v115
	v_mov_b32_e32 v77, v115
	v_mov_b32_e32 v76, v115
	v_mov_b32_e32 v51, v115
	v_mov_b32_e32 v50, v115
	v_mov_b32_e32 v49, v115
	v_mov_b32_e32 v48, v115
	v_mov_b32_e32 v59, v115
	v_mov_b32_e32 v58, v115
	v_mov_b32_e32 v57, v115
	v_mov_b32_e32 v56, v115
	v_mov_b32_e32 v35, v115
	v_mov_b32_e32 v34, v115
	v_mov_b32_e32 v33, v115
	v_mov_b32_e32 v32, v115
	v_mov_b32_e32 v43, v115
	v_mov_b32_e32 v42, v115
	v_mov_b32_e32 v41, v115
	v_mov_b32_e32 v40, v115
	v_mov_b32_e32 v19, v115
	v_mov_b32_e32 v18, v115
	v_mov_b32_e32 v17, v115
	v_mov_b32_e32 v16, v115
	v_mov_b32_e32 v27, v115
	v_mov_b32_e32 v26, v115
	v_mov_b32_e32 v25, v115
	v_mov_b32_e32 v24, v115
	v_mov_b32_e32 v3, v115
	v_mov_b32_e32 v2, v115
	v_mov_b32_e32 v1, v115
	v_mov_b32_e32 v0, v115
	v_mov_b32_e32 v15, v115
	v_mov_b32_e32 v14, v115
	v_mov_b32_e32 v13, v115
	v_mov_b32_e32 v12, v115
	v_mov_b32_e32 v55, v115
	v_mov_b32_e32 v54, v115
	v_mov_b32_e32 v53, v115
	v_mov_b32_e32 v52, v115
	v_mov_b32_e32 v63, v115
	v_mov_b32_e32 v62, v115
	v_mov_b32_e32 v61, v115
	v_mov_b32_e32 v60, v115
	v_mov_b32_e32 v39, v115
	v_mov_b32_e32 v38, v115
	v_mov_b32_e32 v37, v115
	v_mov_b32_e32 v36, v115
	v_mov_b32_e32 v47, v115
	v_mov_b32_e32 v46, v115
	v_mov_b32_e32 v45, v115
	v_mov_b32_e32 v44, v115
	v_mov_b32_e32 v23, v115
	v_mov_b32_e32 v22, v115
	v_mov_b32_e32 v21, v115
	v_mov_b32_e32 v20, v115
	v_mov_b32_e32 v31, v115
	v_mov_b32_e32 v30, v115
	v_mov_b32_e32 v29, v115
	v_mov_b32_e32 v28, v115
	v_mov_b32_e32 v7, v115
	v_mov_b32_e32 v6, v115
	v_mov_b32_e32 v5, v115
	v_mov_b32_e32 v4, v115
	v_mov_b32_e32 v11, v115
	v_mov_b32_e32 v10, v115
	v_mov_b32_e32 v9, v115
	v_mov_b32_e32 v8, v115
	s_branch .LBB0_294

.LBB0_291:
	s_andn2_b64 vcc, exec, s[36:37]
	s_cbranch_vccnz .Lzinit_0
	s_add_u32 s40, s42, 0x80
	s_addc_u32 s41, s43, 0
	s_add_u32 s33, s28, 0x100
	v_mov_b32_e32 v8, 0
	s_addc_u32 s42, s29, 0
	s_mov_b32 s28, 0
	v_mov_b32_e32 v9, v8
	v_mov_b32_e32 v10, v8
	v_mov_b32_e32 v11, v8
	v_mov_b32_e32 v4, v8
	v_mov_b32_e32 v5, v8
	v_mov_b32_e32 v6, v8
	v_mov_b32_e32 v7, v8
	v_mov_b32_e32 v28, v8
	v_mov_b32_e32 v29, v8
	v_mov_b32_e32 v30, v8
	v_mov_b32_e32 v31, v8
	v_mov_b32_e32 v20, v8
	v_mov_b32_e32 v21, v8
	v_mov_b32_e32 v22, v8
	v_mov_b32_e32 v23, v8
	v_mov_b32_e32 v44, v8
	v_mov_b32_e32 v45, v8
	v_mov_b32_e32 v46, v8
	v_mov_b32_e32 v47, v8
	v_mov_b32_e32 v36, v8
	v_mov_b32_e32 v37, v8
	v_mov_b32_e32 v38, v8
	v_mov_b32_e32 v39, v8
	v_mov_b32_e32 v60, v8
	v_mov_b32_e32 v61, v8
	v_mov_b32_e32 v62, v8
	v_mov_b32_e32 v63, v8
	v_mov_b32_e32 v52, v8
	v_mov_b32_e32 v53, v8
	v_mov_b32_e32 v54, v8
	v_mov_b32_e32 v55, v8
	v_mov_b32_e32 v12, v8
	v_mov_b32_e32 v13, v8
	v_mov_b32_e32 v14, v8
	v_mov_b32_e32 v15, v8
	v_mov_b32_e32 v0, v8
	v_mov_b32_e32 v1, v8
	v_mov_b32_e32 v2, v8
	v_mov_b32_e32 v3, v8
	v_mov_b32_e32 v24, v8
	v_mov_b32_e32 v25, v8
	v_mov_b32_e32 v26, v8
	v_mov_b32_e32 v27, v8
	v_mov_b32_e32 v16, v8
	v_mov_b32_e32 v17, v8
	v_mov_b32_e32 v18, v8
	v_mov_b32_e32 v19, v8
	v_mov_b32_e32 v40, v8
	v_mov_b32_e32 v41, v8
	v_mov_b32_e32 v42, v8
	v_mov_b32_e32 v43, v8
	v_mov_b32_e32 v32, v8
	v_mov_b32_e32 v33, v8
	v_mov_b32_e32 v34, v8
	v_mov_b32_e32 v35, v8
	v_mov_b32_e32 v56, v8
	v_mov_b32_e32 v57, v8
	v_mov_b32_e32 v58, v8
	v_mov_b32_e32 v59, v8
	v_mov_b32_e32 v48, v8
	v_mov_b32_e32 v49, v8
	v_mov_b32_e32 v50, v8
	v_mov_b32_e32 v51, v8
	v_mov_b32_e32 v76, v8
	v_mov_b32_e32 v77, v8
	v_mov_b32_e32 v78, v8
	v_mov_b32_e32 v79, v8
	v_mov_b32_e32 v68, v8
	v_mov_b32_e32 v69, v8
	v_mov_b32_e32 v70, v8
	v_mov_b32_e32 v71, v8
	v_mov_b32_e32 v92, v8
	v_mov_b32_e32 v93, v8
	v_mov_b32_e32 v94, v8
	v_mov_b32_e32 v95, v8
	v_mov_b32_e32 v84, v8
	v_mov_b32_e32 v85, v8
	v_mov_b32_e32 v86, v8
	v_mov_b32_e32 v87, v8
	v_mov_b32_e32 v108, v8
	v_mov_b32_e32 v109, v8
	v_mov_b32_e32 v110, v8
	v_mov_b32_e32 v111, v8
	v_mov_b32_e32 v100, v8
	v_mov_b32_e32 v101, v8
	v_mov_b32_e32 v102, v8
	v_mov_b32_e32 v103, v8
	v_mov_b32_e32 v124, v8
	v_mov_b32_e32 v125, v8
	v_mov_b32_e32 v126, v8
	v_mov_b32_e32 v127, v8
	v_mov_b32_e32 v116, v8
	v_mov_b32_e32 v117, v8
	v_mov_b32_e32 v118, v8
	v_mov_b32_e32 v119, v8
	v_mov_b32_e32 v72, v8
	v_mov_b32_e32 v73, v8
	v_mov_b32_e32 v74, v8
	v_mov_b32_e32 v75, v8
	v_mov_b32_e32 v64, v8
	v_mov_b32_e32 v65, v8
	v_mov_b32_e32 v66, v8
	v_mov_b32_e32 v67, v8
	v_mov_b32_e32 v88, v8
	v_mov_b32_e32 v89, v8
	v_mov_b32_e32 v90, v8
	v_mov_b32_e32 v91, v8
	v_mov_b32_e32 v80, v8
	v_mov_b32_e32 v81, v8
	v_mov_b32_e32 v82, v8
	v_mov_b32_e32 v83, v8
	v_mov_b32_e32 v104, v8
	v_mov_b32_e32 v105, v8
	v_mov_b32_e32 v106, v8
	v_mov_b32_e32 v107, v8
	v_mov_b32_e32 v96, v8
	v_mov_b32_e32 v97, v8
	v_mov_b32_e32 v98, v8
	v_mov_b32_e32 v99, v8
	v_mov_b32_e32 v120, v8
	v_mov_b32_e32 v121, v8
	v_mov_b32_e32 v122, v8
	v_mov_b32_e32 v123, v8
	v_mov_b32_e32 v112, v8
	v_mov_b32_e32 v113, v8
	v_mov_b32_e32 v114, v8
	v_mov_b32_e32 v115, v8

.Lzinit_1:
	v_mov_b32_e32 v123, 0
	v_mov_b32_e32 v122, v123
	v_mov_b32_e32 v121, v123
	v_mov_b32_e32 v120, v123
	v_mov_b32_e32 v127, v123
	v_mov_b32_e32 v126, v123
	v_mov_b32_e32 v125, v123
	v_mov_b32_e32 v124, v123
	v_mov_b32_e32 v111, v123
	v_mov_b32_e32 v110, v123
	v_mov_b32_e32 v109, v123
	v_mov_b32_e32 v108, v123
	v_mov_b32_e32 v107, v123
	v_mov_b32_e32 v106, v123
	v_mov_b32_e32 v105, v123
	v_mov_b32_e32 v104, v123
	v_mov_b32_e32 v95, v123
	v_mov_b32_e32 v94, v123
	v_mov_b32_e32 v93, v123
	v_mov_b32_e32 v92, v123
	v_mov_b32_e32 v91, v123
	v_mov_b32_e32 v90, v123
	v_mov_b32_e32 v89, v123
	v_mov_b32_e32 v88, v123
	v_mov_b32_e32 v79, v123
	v_mov_b32_e32 v78, v123
	v_mov_b32_e32 v77, v123
	v_mov_b32_e32 v76, v123
	v_mov_b32_e32 v75, v123
	v_mov_b32_e32 v74, v123
	v_mov_b32_e32 v73, v123
	v_mov_b32_e32 v72, v123
	v_mov_b32_e32 v119, v123
	v_mov_b32_e32 v118, v123
	v_mov_b32_e32 v117, v123
	v_mov_b32_e32 v116, v123
	v_mov_b32_e32 v115, v123
	v_mov_b32_e32 v114, v123
	v_mov_b32_e32 v113, v123
	v_mov_b32_e32 v112, v123
	v_mov_b32_e32 v103, v123
	v_mov_b32_e32 v102, v123
	v_mov_b32_e32 v101, v123
	v_mov_b32_e32 v100, v123
	v_mov_b32_e32 v99, v123
	v_mov_b32_e32 v98, v123
	v_mov_b32_e32 v97, v123
	v_mov_b32_e32 v96, v123
	v_mov_b32_e32 v87, v123
	v_mov_b32_e32 v86, v123
	v_mov_b32_e32 v85, v123
	v_mov_b32_e32 v84, v123
	v_mov_b32_e32 v83, v123
	v_mov_b32_e32 v82, v123
	v_mov_b32_e32 v81, v123
	v_mov_b32_e32 v80, v123
	v_mov_b32_e32 v71, v123
	v_mov_b32_e32 v70, v123
	v_mov_b32_e32 v69, v123
	v_mov_b32_e32 v68, v123
	v_mov_b32_e32 v67, v123
	v_mov_b32_e32 v66, v123
	v_mov_b32_e32 v65, v123
	v_mov_b32_e32 v64, v123
	v_mov_b32_e32 v63, v123
	v_mov_b32_e32 v62, v123
	v_mov_b32_e32 v61, v123
	v_mov_b32_e32 v60, v123
	v_mov_b32_e32 v59, v123
	v_mov_b32_e32 v58, v123
	v_mov_b32_e32 v57, v123
	v_mov_b32_e32 v56, v123
	v_mov_b32_e32 v47, v123
	v_mov_b32_e32 v46, v123
	v_mov_b32_e32 v45, v123
	v_mov_b32_e32 v44, v123
	v_mov_b32_e32 v43, v123
	v_mov_b32_e32 v42, v123
	v_mov_b32_e32 v41, v123
	v_mov_b32_e32 v40, v123
	v_mov_b32_e32 v31, v123
	v_mov_b32_e32 v30, v123
	v_mov_b32_e32 v29, v123
	v_mov_b32_e32 v28, v123
	v_mov_b32_e32 v27, v123
	v_mov_b32_e32 v26, v123
	v_mov_b32_e32 v25, v123
	v_mov_b32_e32 v24, v123
	v_mov_b32_e32 v15, v123
	v_mov_b32_e32 v14, v123
	v_mov_b32_e32 v13, v123
	v_mov_b32_e32 v12, v123
	v_mov_b32_e32 v11, v123
	v_mov_b32_e32 v10, v123
	v_mov_b32_e32 v9, v123
	v_mov_b32_e32 v8, v123
	v_mov_b32_e32 v55, v123
	v_mov_b32_e32 v54, v123
	v_mov_b32_e32 v53, v123
	v_mov_b32_e32 v52, v123
	v_mov_b32_e32 v51, v123
	v_mov_b32_e32 v50, v123
	v_mov_b32_e32 v49, v123
	v_mov_b32_e32 v48, v123
	v_mov_b32_e32 v39, v123
	v_mov_b32_e32 v38, v123
	v_mov_b32_e32 v37, v123
	v_mov_b32_e32 v36, v123
	v_mov_b32_e32 v35, v123
	v_mov_b32_e32 v34, v123
	v_mov_b32_e32 v33, v123
	v_mov_b32_e32 v32, v123
	v_mov_b32_e32 v23, v123
	v_mov_b32_e32 v22, v123
	v_mov_b32_e32 v21, v123
	v_mov_b32_e32 v20, v123
	v_mov_b32_e32 v19, v123
	v_mov_b32_e32 v18, v123
	v_mov_b32_e32 v17, v123
	v_mov_b32_e32 v16, v123
	v_mov_b32_e32 v7, v123
	v_mov_b32_e32 v6, v123
	v_mov_b32_e32 v5, v123
	v_mov_b32_e32 v4, v123
	v_mov_b32_e32 v3, v123
	v_mov_b32_e32 v2, v123
	v_mov_b32_e32 v1, v123
	v_mov_b32_e32 v0, v123
	s_branch .LBB0_766

.LBB0_762:
	s_andn2_b64 vcc, exec, s[36:37]
	s_cbranch_vccnz .Lzinit_1
	s_add_u32 s50, s50, 0x80
	s_addc_u32 s51, s51, 0
	s_add_u32 s33, s28, 0x100
	v_mov_b32_e32 v0, 0
	s_addc_u32 s71, s29, 0
	s_mov_b32 s28, 0
	v_mov_b32_e32 v1, v0
	v_mov_b32_e32 v2, v0
	v_mov_b32_e32 v3, v0
	v_mov_b32_e32 v4, v0
	v_mov_b32_e32 v5, v0
	v_mov_b32_e32 v6, v0
	v_mov_b32_e32 v7, v0
	v_mov_b32_e32 v16, v0
	v_mov_b32_e32 v17, v0
	v_mov_b32_e32 v18, v0
	v_mov_b32_e32 v19, v0
	v_mov_b32_e32 v20, v0
	v_mov_b32_e32 v21, v0
	v_mov_b32_e32 v22, v0
	v_mov_b32_e32 v23, v0
	v_mov_b32_e32 v32, v0
	v_mov_b32_e32 v33, v0
	v_mov_b32_e32 v34, v0
	v_mov_b32_e32 v35, v0
	v_mov_b32_e32 v36, v0
	v_mov_b32_e32 v37, v0
	v_mov_b32_e32 v38, v0
	v_mov_b32_e32 v39, v0
	v_mov_b32_e32 v48, v0
	v_mov_b32_e32 v49, v0
	v_mov_b32_e32 v50, v0
	v_mov_b32_e32 v51, v0
	v_mov_b32_e32 v52, v0
	v_mov_b32_e32 v53, v0
	v_mov_b32_e32 v54, v0
	v_mov_b32_e32 v55, v0
	v_mov_b32_e32 v8, v0
	v_mov_b32_e32 v9, v0
	v_mov_b32_e32 v10, v0
	v_mov_b32_e32 v11, v0
	v_mov_b32_e32 v12, v0
	v_mov_b32_e32 v13, v0
	v_mov_b32_e32 v14, v0
	v_mov_b32_e32 v15, v0
	v_mov_b32_e32 v24, v0
	v_mov_b32_e32 v25, v0
	v_mov_b32_e32 v26, v0
	v_mov_b32_e32 v27, v0
	v_mov_b32_e32 v28, v0
	v_mov_b32_e32 v29, v0
	v_mov_b32_e32 v30, v0
	v_mov_b32_e32 v31, v0
	v_mov_b32_e32 v40, v0
	v_mov_b32_e32 v41, v0
	v_mov_b32_e32 v42, v0
	v_mov_b32_e32 v43, v0
	v_mov_b32_e32 v44, v0
	v_mov_b32_e32 v45, v0
	v_mov_b32_e32 v46, v0
	v_mov_b32_e32 v47, v0
	v_mov_b32_e32 v56, v0
	v_mov_b32_e32 v57, v0
	v_mov_b32_e32 v58, v0
	v_mov_b32_e32 v59, v0
	v_mov_b32_e32 v60, v0
	v_mov_b32_e32 v61, v0
	v_mov_b32_e32 v62, v0
	v_mov_b32_e32 v63, v0
	v_mov_b32_e32 v64, v0
	v_mov_b32_e32 v65, v0
	v_mov_b32_e32 v66, v0
	v_mov_b32_e32 v67, v0
	v_mov_b32_e32 v68, v0
	v_mov_b32_e32 v69, v0
	v_mov_b32_e32 v70, v0
	v_mov_b32_e32 v71, v0
	v_mov_b32_e32 v80, v0
	v_mov_b32_e32 v81, v0
	v_mov_b32_e32 v82, v0
	v_mov_b32_e32 v83, v0
	v_mov_b32_e32 v84, v0
	v_mov_b32_e32 v85, v0
	v_mov_b32_e32 v86, v0
	v_mov_b32_e32 v87, v0
	v_mov_b32_e32 v96, v0
	v_mov_b32_e32 v97, v0
	v_mov_b32_e32 v98, v0
	v_mov_b32_e32 v99, v0
	v_mov_b32_e32 v100, v0
	v_mov_b32_e32 v101, v0
	v_mov_b32_e32 v102, v0
	v_mov_b32_e32 v103, v0
	v_mov_b32_e32 v112, v0
	v_mov_b32_e32 v113, v0
	v_mov_b32_e32 v114, v0
	v_mov_b32_e32 v115, v0
	v_mov_b32_e32 v116, v0
	v_mov_b32_e32 v117, v0
	v_mov_b32_e32 v118, v0
	v_mov_b32_e32 v119, v0
	v_mov_b32_e32 v72, v0
	v_mov_b32_e32 v73, v0
	v_mov_b32_e32 v74, v0
	v_mov_b32_e32 v75, v0
	v_mov_b32_e32 v76, v0
	v_mov_b32_e32 v77, v0
	v_mov_b32_e32 v78, v0
	v_mov_b32_e32 v79, v0
	v_mov_b32_e32 v88, v0
	v_mov_b32_e32 v89, v0
	v_mov_b32_e32 v90, v0
	v_mov_b32_e32 v91, v0
	v_mov_b32_e32 v92, v0
	v_mov_b32_e32 v93, v0
	v_mov_b32_e32 v94, v0
	v_mov_b32_e32 v95, v0
	v_mov_b32_e32 v104, v0
	v_mov_b32_e32 v105, v0
	v_mov_b32_e32 v106, v0
	v_mov_b32_e32 v107, v0
	v_mov_b32_e32 v108, v0
	v_mov_b32_e32 v109, v0
	v_mov_b32_e32 v110, v0
	v_mov_b32_e32 v111, v0
	v_mov_b32_e32 v124, v0
	v_mov_b32_e32 v125, v0
	v_mov_b32_e32 v126, v0
	v_mov_b32_e32 v127, v0
	v_mov_b32_e32 v120, v0
	v_mov_b32_e32 v121, v0
	v_mov_b32_e32 v122, v0
	v_mov_b32_e32 v123, v0

.Lzinit_2:
	v_mov_b32_e32 v141, 0
	v_mov_b32_e32 v140, v141
	v_mov_b32_e32 v139, v141
	v_mov_b32_e32 v138, v141
	v_mov_b32_e32 v145, v141
	v_mov_b32_e32 v144, v141
	v_mov_b32_e32 v143, v141
	v_mov_b32_e32 v142, v141
	v_mov_b32_e32 v127, v141
	v_mov_b32_e32 v126, v141
	v_mov_b32_e32 v125, v141
	v_mov_b32_e32 v124, v141
	v_mov_b32_e32 v123, v141
	v_mov_b32_e32 v122, v141
	v_mov_b32_e32 v121, v141
	v_mov_b32_e32 v120, v141
	v_mov_b32_e32 v111, v141
	v_mov_b32_e32 v110, v141
	v_mov_b32_e32 v109, v141
	v_mov_b32_e32 v108, v141
	v_mov_b32_e32 v107, v141
	v_mov_b32_e32 v106, v141
	v_mov_b32_e32 v105, v141
	v_mov_b32_e32 v104, v141
	v_mov_b32_e32 v95, v141
	v_mov_b32_e32 v94, v141
	v_mov_b32_e32 v93, v141
	v_mov_b32_e32 v92, v141
	v_mov_b32_e32 v91, v141
	v_mov_b32_e32 v90, v141
	v_mov_b32_e32 v89, v141
	v_mov_b32_e32 v88, v141
	v_mov_b32_e32 v137, v141
	v_mov_b32_e32 v136, v141
	v_mov_b32_e32 v135, v141
	v_mov_b32_e32 v134, v141
	v_mov_b32_e32 v133, v141
	v_mov_b32_e32 v132, v141
	v_mov_b32_e32 v131, v141
	v_mov_b32_e32 v130, v141
	v_mov_b32_e32 v119, v141
	v_mov_b32_e32 v118, v141
	v_mov_b32_e32 v117, v141
	v_mov_b32_e32 v116, v141
	v_mov_b32_e32 v115, v141
	v_mov_b32_e32 v114, v141
	v_mov_b32_e32 v113, v141
	v_mov_b32_e32 v112, v141
	v_mov_b32_e32 v103, v141
	v_mov_b32_e32 v102, v141
	v_mov_b32_e32 v101, v141
	v_mov_b32_e32 v100, v141
	v_mov_b32_e32 v99, v141
	v_mov_b32_e32 v98, v141
	v_mov_b32_e32 v97, v141
	v_mov_b32_e32 v96, v141
	v_mov_b32_e32 v87, v141
	v_mov_b32_e32 v86, v141
	v_mov_b32_e32 v85, v141
	v_mov_b32_e32 v84, v141
	v_mov_b32_e32 v83, v141
	v_mov_b32_e32 v82, v141
	v_mov_b32_e32 v81, v141
	v_mov_b32_e32 v80, v141
	v_mov_b32_e32 v79, v141
	v_mov_b32_e32 v78, v141
	v_mov_b32_e32 v77, v141
	v_mov_b32_e32 v76, v141
	v_mov_b32_e32 v75, v141
	v_mov_b32_e32 v74, v141
	v_mov_b32_e32 v73, v141
	v_mov_b32_e32 v72, v141
	v_mov_b32_e32 v63, v141
	v_mov_b32_e32 v62, v141
	v_mov_b32_e32 v61, v141
	v_mov_b32_e32 v60, v141
	v_mov_b32_e32 v59, v141
	v_mov_b32_e32 v58, v141
	v_mov_b32_e32 v57, v141
	v_mov_b32_e32 v56, v141
	v_mov_b32_e32 v47, v141
	v_mov_b32_e32 v46, v141
	v_mov_b32_e32 v45, v141
	v_mov_b32_e32 v44, v141
	v_mov_b32_e32 v39, v141
	v_mov_b32_e32 v38, v141
	v_mov_b32_e32 v37, v141
	v_mov_b32_e32 v36, v141
	v_mov_b32_e32 v15, v141
	v_mov_b32_e32 v14, v141
	v_mov_b32_e32 v13, v141
	v_mov_b32_e32 v12, v141
	v_mov_b32_e32 v11, v141
	v_mov_b32_e32 v10, v141
	v_mov_b32_e32 v9, v141
	v_mov_b32_e32 v8, v141
	v_mov_b32_e32 v71, v141
	v_mov_b32_e32 v70, v141
	v_mov_b32_e32 v69, v141
	v_mov_b32_e32 v68, v141
	v_mov_b32_e32 v67, v141
	v_mov_b32_e32 v66, v141
	v_mov_b32_e32 v65, v141
	v_mov_b32_e32 v64, v141
	v_mov_b32_e32 v55, v141
	v_mov_b32_e32 v54, v141
	v_mov_b32_e32 v53, v141
	v_mov_b32_e32 v52, v141
	v_mov_b32_e32 v51, v141
	v_mov_b32_e32 v50, v141
	v_mov_b32_e32 v49, v141
	v_mov_b32_e32 v48, v141
	v_mov_b32_e32 v31, v141
	v_mov_b32_e32 v30, v141
	v_mov_b32_e32 v29, v141
	v_mov_b32_e32 v28, v141
	v_mov_b32_e32 v27, v141
	v_mov_b32_e32 v26, v141
	v_mov_b32_e32 v25, v141
	v_mov_b32_e32 v24, v141
	v_mov_b32_e32 v7, v141
	v_mov_b32_e32 v6, v141
	v_mov_b32_e32 v5, v141
	v_mov_b32_e32 v4, v141
	v_mov_b32_e32 v3, v141
	v_mov_b32_e32 v2, v141
	v_mov_b32_e32 v1, v141
	v_mov_b32_e32 v0, v141
	s_branch .LBB0_900

.LBB0_897:
	s_andn2_b64 vcc, exec, s[36:37]
	s_cbranch_vccnz .Lzinit_2
	s_add_u32 s42, s44, 0x80
	s_addc_u32 s43, s45, 0
	s_add_u32 s7, s28, 0x100
	v_mov_b32_e32 v0, 0
	s_addc_u32 s18, s29, 0
	s_mov_b32 s28, 0
	v_mov_b32_e32 v1, v0
	v_mov_b32_e32 v2, v0
	v_mov_b32_e32 v3, v0
	v_mov_b32_e32 v4, v0
	v_mov_b32_e32 v5, v0
	v_mov_b32_e32 v6, v0
	v_mov_b32_e32 v7, v0
	v_mov_b32_e32 v24, v0
	v_mov_b32_e32 v25, v0
	v_mov_b32_e32 v26, v0
	v_mov_b32_e32 v27, v0
	v_mov_b32_e32 v28, v0
	v_mov_b32_e32 v29, v0
	v_mov_b32_e32 v30, v0
	v_mov_b32_e32 v31, v0
	v_mov_b32_e32 v48, v0
	v_mov_b32_e32 v49, v0
	v_mov_b32_e32 v50, v0
	v_mov_b32_e32 v51, v0
	v_mov_b32_e32 v52, v0
	v_mov_b32_e32 v53, v0
	v_mov_b32_e32 v54, v0
	v_mov_b32_e32 v55, v0
	v_mov_b32_e32 v64, v0
	v_mov_b32_e32 v65, v0
	v_mov_b32_e32 v66, v0
	v_mov_b32_e32 v67, v0
	v_mov_b32_e32 v68, v0
	v_mov_b32_e32 v69, v0
	v_mov_b32_e32 v70, v0
	v_mov_b32_e32 v71, v0
	v_mov_b32_e32 v8, v0
	v_mov_b32_e32 v9, v0
	v_mov_b32_e32 v10, v0
	v_mov_b32_e32 v11, v0
	v_mov_b32_e32 v12, v0
	v_mov_b32_e32 v13, v0
	v_mov_b32_e32 v14, v0
	v_mov_b32_e32 v15, v0
	v_mov_b32_e32 v36, v0
	v_mov_b32_e32 v37, v0
	v_mov_b32_e32 v38, v0
	v_mov_b32_e32 v39, v0
	v_mov_b32_e32 v44, v0
	v_mov_b32_e32 v45, v0
	v_mov_b32_e32 v46, v0
	v_mov_b32_e32 v47, v0
	v_mov_b32_e32 v56, v0
	v_mov_b32_e32 v57, v0
	v_mov_b32_e32 v58, v0
	v_mov_b32_e32 v59, v0
	v_mov_b32_e32 v60, v0
	v_mov_b32_e32 v61, v0
	v_mov_b32_e32 v62, v0
	v_mov_b32_e32 v63, v0
	v_mov_b32_e32 v72, v0
	v_mov_b32_e32 v73, v0
	v_mov_b32_e32 v74, v0
	v_mov_b32_e32 v75, v0
	v_mov_b32_e32 v76, v0
	v_mov_b32_e32 v77, v0
	v_mov_b32_e32 v78, v0
	v_mov_b32_e32 v79, v0
	v_mov_b32_e32 v80, v0
	v_mov_b32_e32 v81, v0
	v_mov_b32_e32 v82, v0
	v_mov_b32_e32 v83, v0
	v_mov_b32_e32 v84, v0
	v_mov_b32_e32 v85, v0
	v_mov_b32_e32 v86, v0
	v_mov_b32_e32 v87, v0
	v_mov_b32_e32 v96, v0
	v_mov_b32_e32 v97, v0
	v_mov_b32_e32 v98, v0
	v_mov_b32_e32 v99, v0
	v_mov_b32_e32 v100, v0
	v_mov_b32_e32 v101, v0
	v_mov_b32_e32 v102, v0
	v_mov_b32_e32 v103, v0
	v_mov_b32_e32 v112, v0
	v_mov_b32_e32 v113, v0
	v_mov_b32_e32 v114, v0
	v_mov_b32_e32 v115, v0
	v_mov_b32_e32 v116, v0
	v_mov_b32_e32 v117, v0
	v_mov_b32_e32 v118, v0
	v_mov_b32_e32 v119, v0
	v_mov_b32_e32 v130, v0
	v_mov_b32_e32 v131, v0
	v_mov_b32_e32 v132, v0
	v_mov_b32_e32 v133, v0
	v_mov_b32_e32 v134, v0
	v_mov_b32_e32 v135, v0
	v_mov_b32_e32 v136, v0
	v_mov_b32_e32 v137, v0
	v_mov_b32_e32 v88, v0
	v_mov_b32_e32 v89, v0
	v_mov_b32_e32 v90, v0
	v_mov_b32_e32 v91, v0
	v_mov_b32_e32 v92, v0
	v_mov_b32_e32 v93, v0
	v_mov_b32_e32 v94, v0
	v_mov_b32_e32 v95, v0
	v_mov_b32_e32 v104, v0
	v_mov_b32_e32 v105, v0
	v_mov_b32_e32 v106, v0
	v_mov_b32_e32 v107, v0
	v_mov_b32_e32 v108, v0
	v_mov_b32_e32 v109, v0
	v_mov_b32_e32 v110, v0
	v_mov_b32_e32 v111, v0
	v_mov_b32_e32 v120, v0
	v_mov_b32_e32 v121, v0
	v_mov_b32_e32 v122, v0
	v_mov_b32_e32 v123, v0
	v_mov_b32_e32 v124, v0
	v_mov_b32_e32 v125, v0
	v_mov_b32_e32 v126, v0
	v_mov_b32_e32 v127, v0
	v_mov_b32_e32 v142, v0
	v_mov_b32_e32 v143, v0
	v_mov_b32_e32 v144, v0
	v_mov_b32_e32 v145, v0
	v_mov_b32_e32 v138, v0
	v_mov_b32_e32 v139, v0
	v_mov_b32_e32 v140, v0
	v_mov_b32_e32 v141, v0

.Lzinit_3:
	v_mov_b32_e32 v173, 0
	v_mov_b32_e32 v172, v173
	v_mov_b32_e32 v171, v173
	v_mov_b32_e32 v170, v173
	v_mov_b32_e32 v75, v173
	v_mov_b32_e32 v74, v173
	v_mov_b32_e32 v73, v173
	v_mov_b32_e32 v72, v173
	v_mov_b32_e32 v165, v173
	v_mov_b32_e32 v164, v173
	v_mov_b32_e32 v163, v173
	v_mov_b32_e32 v162, v173
	v_mov_b32_e32 v63, v173
	v_mov_b32_e32 v62, v173
	v_mov_b32_e32 v61, v173
	v_mov_b32_e32 v60, v173
	v_mov_b32_e32 v157, v173
	v_mov_b32_e32 v156, v173
	v_mov_b32_e32 v155, v173
	v_mov_b32_e32 v154, v173
	v_mov_b32_e32 v51, v173
	v_mov_b32_e32 v50, v173
	v_mov_b32_e32 v49, v173
	v_mov_b32_e32 v48, v173
	v_mov_b32_e32 v137, v173
	v_mov_b32_e32 v136, v173
	v_mov_b32_e32 v135, v173
	v_mov_b32_e32 v134, v173
	v_mov_b32_e32 v39, v173
	v_mov_b32_e32 v38, v173
	v_mov_b32_e32 v37, v173
	v_mov_b32_e32 v36, v173
	v_mov_b32_e32 v169, v173
	v_mov_b32_e32 v168, v173
	v_mov_b32_e32 v167, v173
	v_mov_b32_e32 v166, v173
	v_mov_b32_e32 v71, v173
	v_mov_b32_e32 v70, v173
	v_mov_b32_e32 v69, v173
	v_mov_b32_e32 v68, v173
	v_mov_b32_e32 v161, v173
	v_mov_b32_e32 v160, v173
	v_mov_b32_e32 v159, v173
	v_mov_b32_e32 v158, v173
	v_mov_b32_e32 v59, v173
	v_mov_b32_e32 v58, v173
	v_mov_b32_e32 v57, v173
	v_mov_b32_e32 v56, v173
	v_mov_b32_e32 v145, v173
	v_mov_b32_e32 v144, v173
	v_mov_b32_e32 v143, v173
	v_mov_b32_e32 v142, v173
	v_mov_b32_e32 v47, v173
	v_mov_b32_e32 v46, v173
	v_mov_b32_e32 v45, v173
	v_mov_b32_e32 v44, v173
	v_mov_b32_e32 v133, v173
	v_mov_b32_e32 v132, v173
	v_mov_b32_e32 v131, v173
	v_mov_b32_e32 v130, v173
	v_mov_b32_e32 v35, v173
	v_mov_b32_e32 v34, v173
	v_mov_b32_e32 v33, v173
	v_mov_b32_e32 v32, v173
	v_mov_b32_e32 v123, v173
	v_mov_b32_e32 v122, v173
	v_mov_b32_e32 v121, v173
	v_mov_b32_e32 v120, v173
	v_mov_b32_e32 v31, v173
	v_mov_b32_e32 v30, v173
	v_mov_b32_e32 v29, v173
	v_mov_b32_e32 v28, v173
	v_mov_b32_e32 v111, v173
	v_mov_b32_e32 v110, v173
	v_mov_b32_e32 v109, v173
	v_mov_b32_e32 v108, v173
	v_mov_b32_e32 v23, v173
	v_mov_b32_e32 v22, v173
	v_mov_b32_e32 v21, v173
	v_mov_b32_e32 v20, v173
	v_mov_b32_e32 v99, v173
	v_mov_b32_e32 v98, v173
	v_mov_b32_e32 v97, v173
	v_mov_b32_e32 v96, v173
	v_mov_b32_e32 v15, v173
	v_mov_b32_e32 v14, v173
	v_mov_b32_e32 v13, v173
	v_mov_b32_e32 v12, v173
	v_mov_b32_e32 v87, v173
	v_mov_b32_e32 v86, v173
	v_mov_b32_e32 v85, v173
	v_mov_b32_e32 v84, v173
	v_mov_b32_e32 v7, v173
	v_mov_b32_e32 v6, v173
	v_mov_b32_e32 v5, v173
	v_mov_b32_e32 v4, v173
	v_mov_b32_e32 v119, v173
	v_mov_b32_e32 v118, v173
	v_mov_b32_e32 v117, v173
	v_mov_b32_e32 v116, v173
	v_mov_b32_e32 v27, v173
	v_mov_b32_e32 v26, v173
	v_mov_b32_e32 v25, v173
	v_mov_b32_e32 v24, v173
	v_mov_b32_e32 v107, v173
	v_mov_b32_e32 v106, v173
	v_mov_b32_e32 v105, v173
	v_mov_b32_e32 v104, v173
	v_mov_b32_e32 v19, v173
	v_mov_b32_e32 v18, v173
	v_mov_b32_e32 v17, v173
	v_mov_b32_e32 v16, v173
	v_mov_b32_e32 v95, v173
	v_mov_b32_e32 v94, v173
	v_mov_b32_e32 v93, v173
	v_mov_b32_e32 v92, v173
	v_mov_b32_e32 v11, v173
	v_mov_b32_e32 v10, v173
	v_mov_b32_e32 v9, v173
	v_mov_b32_e32 v8, v173
	v_mov_b32_e32 v83, v173
	v_mov_b32_e32 v82, v173
	v_mov_b32_e32 v81, v173
	v_mov_b32_e32 v80, v173
	v_mov_b32_e32 v3, v173
	v_mov_b32_e32 v2, v173
	v_mov_b32_e32 v1, v173
	v_mov_b32_e32 v0, v173
	s_branch .LBB0_1167

.LBB0_1163:
	s_andn2_b64 vcc, exec, s[46:47]
	s_cbranch_vccnz .Lzinit_3
	s_add_u32 s58, s58, 0x80
	s_addc_u32 s59, s59, 0
	s_add_u32 s18, s28, 0x100
	v_mov_b32_e32 v0, 0
	s_addc_u32 s33, s29, 0
	s_mov_b32 s28, 0
	v_mov_b32_e32 v1, v0
	v_mov_b32_e32 v2, v0
	v_mov_b32_e32 v3, v0
	v_mov_b32_e32 v80, v0
	v_mov_b32_e32 v81, v0
	v_mov_b32_e32 v82, v0
	v_mov_b32_e32 v83, v0
	v_mov_b32_e32 v8, v0
	v_mov_b32_e32 v9, v0
	v_mov_b32_e32 v10, v0
	v_mov_b32_e32 v11, v0
	v_mov_b32_e32 v92, v0
	v_mov_b32_e32 v93, v0
	v_mov_b32_e32 v94, v0
	v_mov_b32_e32 v95, v0
	v_mov_b32_e32 v16, v0
	v_mov_b32_e32 v17, v0
	v_mov_b32_e32 v18, v0
	v_mov_b32_e32 v19, v0
	v_mov_b32_e32 v104, v0
	v_mov_b32_e32 v105, v0
	v_mov_b32_e32 v106, v0
	v_mov_b32_e32 v107, v0
	v_mov_b32_e32 v24, v0
	v_mov_b32_e32 v25, v0
	v_mov_b32_e32 v26, v0
	v_mov_b32_e32 v27, v0
	v_mov_b32_e32 v116, v0
	v_mov_b32_e32 v117, v0
	v_mov_b32_e32 v118, v0
	v_mov_b32_e32 v119, v0
	v_mov_b32_e32 v4, v0
	v_mov_b32_e32 v5, v0
	v_mov_b32_e32 v6, v0
	v_mov_b32_e32 v7, v0
	v_mov_b32_e32 v84, v0
	v_mov_b32_e32 v85, v0
	v_mov_b32_e32 v86, v0
	v_mov_b32_e32 v87, v0
	v_mov_b32_e32 v12, v0
	v_mov_b32_e32 v13, v0
	v_mov_b32_e32 v14, v0
	v_mov_b32_e32 v15, v0
	v_mov_b32_e32 v96, v0
	v_mov_b32_e32 v97, v0
	v_mov_b32_e32 v98, v0
	v_mov_b32_e32 v99, v0
	v_mov_b32_e32 v20, v0
	v_mov_b32_e32 v21, v0
	v_mov_b32_e32 v22, v0
	v_mov_b32_e32 v23, v0
	v_mov_b32_e32 v108, v0
	v_mov_b32_e32 v109, v0
	v_mov_b32_e32 v110, v0
	v_mov_b32_e32 v111, v0
	v_mov_b32_e32 v28, v0
	v_mov_b32_e32 v29, v0
	v_mov_b32_e32 v30, v0
	v_mov_b32_e32 v31, v0
	v_mov_b32_e32 v120, v0
	v_mov_b32_e32 v121, v0
	v_mov_b32_e32 v122, v0
	v_mov_b32_e32 v123, v0
	v_mov_b32_e32 v32, v0
	v_mov_b32_e32 v33, v0
	v_mov_b32_e32 v34, v0
	v_mov_b32_e32 v35, v0
	v_mov_b32_e32 v130, v0
	v_mov_b32_e32 v131, v0
	v_mov_b32_e32 v132, v0
	v_mov_b32_e32 v133, v0
	v_mov_b32_e32 v44, v0
	v_mov_b32_e32 v45, v0
	v_mov_b32_e32 v46, v0
	v_mov_b32_e32 v47, v0
	v_mov_b32_e32 v142, v0
	v_mov_b32_e32 v143, v0
	v_mov_b32_e32 v144, v0
	v_mov_b32_e32 v145, v0
	v_mov_b32_e32 v56, v0
	v_mov_b32_e32 v57, v0
	v_mov_b32_e32 v58, v0
	v_mov_b32_e32 v59, v0
	v_mov_b32_e32 v158, v0
	v_mov_b32_e32 v159, v0
	v_mov_b32_e32 v160, v0
	v_mov_b32_e32 v161, v0
	v_mov_b32_e32 v68, v0
	v_mov_b32_e32 v69, v0
	v_mov_b32_e32 v70, v0
	v_mov_b32_e32 v71, v0
	v_mov_b32_e32 v166, v0
	v_mov_b32_e32 v167, v0
	v_mov_b32_e32 v168, v0
	v_mov_b32_e32 v169, v0
	v_mov_b32_e32 v36, v0
	v_mov_b32_e32 v37, v0
	v_mov_b32_e32 v38, v0
	v_mov_b32_e32 v39, v0
	v_mov_b32_e32 v134, v0
	v_mov_b32_e32 v135, v0
	v_mov_b32_e32 v136, v0
	v_mov_b32_e32 v137, v0
	v_mov_b32_e32 v48, v0
	v_mov_b32_e32 v49, v0
	v_mov_b32_e32 v50, v0
	v_mov_b32_e32 v51, v0
	v_mov_b32_e32 v154, v0
	v_mov_b32_e32 v155, v0
	v_mov_b32_e32 v156, v0
	v_mov_b32_e32 v157, v0
	v_mov_b32_e32 v60, v0
	v_mov_b32_e32 v61, v0
	v_mov_b32_e32 v62, v0
	v_mov_b32_e32 v63, v0
	v_mov_b32_e32 v162, v0
	v_mov_b32_e32 v163, v0
	v_mov_b32_e32 v164, v0
	v_mov_b32_e32 v165, v0
	v_mov_b32_e32 v72, v0
	v_mov_b32_e32 v73, v0
	v_mov_b32_e32 v74, v0
	v_mov_b32_e32 v75, v0
	v_mov_b32_e32 v170, v0
	v_mov_b32_e32 v171, v0
	v_mov_b32_e32 v172, v0
	v_mov_b32_e32 v173, v0

.LBB0_1644:
	s_andn2_b64 vcc, exec, s[26:27]
	s_cbranch_vccnz .Lzinit_4
	s_add_u32 s46, s46, 0x80
	s_addc_u32 s47, s47, 0
	s_add_u32 s33, s28, 0x100
	v_mov_b32_e32 v0, 0
	s_addc_u32 s67, s29, 0
	s_mov_b32 s28, 0
	v_mov_b32_e32 v1, v0
	v_mov_b32_e32 v2, v0
	v_mov_b32_e32 v3, v0
	v_mov_b32_e32 v4, v0
	v_mov_b32_e32 v5, v0
	v_mov_b32_e32 v6, v0
	v_mov_b32_e32 v7, v0
	v_mov_b32_e32 v16, v0
	v_mov_b32_e32 v17, v0
	v_mov_b32_e32 v18, v0
	v_mov_b32_e32 v19, v0
	v_mov_b32_e32 v20, v0
	v_mov_b32_e32 v21, v0
	v_mov_b32_e32 v22, v0
	v_mov_b32_e32 v23, v0
	v_mov_b32_e32 v32, v0
	v_mov_b32_e32 v33, v0
	v_mov_b32_e32 v34, v0
	v_mov_b32_e32 v35, v0
	v_mov_b32_e32 v36, v0
	v_mov_b32_e32 v37, v0
	v_mov_b32_e32 v38, v0
	v_mov_b32_e32 v39, v0
	v_mov_b32_e32 v48, v0
	v_mov_b32_e32 v49, v0
	v_mov_b32_e32 v50, v0
	v_mov_b32_e32 v51, v0
	v_mov_b32_e32 v52, v0
	v_mov_b32_e32 v53, v0
	v_mov_b32_e32 v54, v0
	v_mov_b32_e32 v55, v0
	v_mov_b32_e32 v8, v0
	v_mov_b32_e32 v9, v0
	v_mov_b32_e32 v10, v0
	v_mov_b32_e32 v11, v0
	v_mov_b32_e32 v12, v0
	v_mov_b32_e32 v13, v0
	v_mov_b32_e32 v14, v0
	v_mov_b32_e32 v15, v0
	v_mov_b32_e32 v24, v0
	v_mov_b32_e32 v25, v0
	v_mov_b32_e32 v26, v0
	v_mov_b32_e32 v27, v0
	v_mov_b32_e32 v28, v0
	v_mov_b32_e32 v29, v0
	v_mov_b32_e32 v30, v0
	v_mov_b32_e32 v31, v0
	v_mov_b32_e32 v40, v0
	v_mov_b32_e32 v41, v0
	v_mov_b32_e32 v42, v0
	v_mov_b32_e32 v43, v0
	v_mov_b32_e32 v44, v0
	v_mov_b32_e32 v45, v0
	v_mov_b32_e32 v46, v0
	v_mov_b32_e32 v47, v0
	v_mov_b32_e32 v56, v0
	v_mov_b32_e32 v57, v0
	v_mov_b32_e32 v58, v0
	v_mov_b32_e32 v59, v0
	v_mov_b32_e32 v60, v0
	v_mov_b32_e32 v61, v0
	v_mov_b32_e32 v62, v0
	v_mov_b32_e32 v63, v0
	v_mov_b32_e32 v64, v0
	v_mov_b32_e32 v65, v0
	v_mov_b32_e32 v66, v0
	v_mov_b32_e32 v67, v0
	v_mov_b32_e32 v68, v0
	v_mov_b32_e32 v69, v0
	v_mov_b32_e32 v70, v0
	v_mov_b32_e32 v71, v0
	v_mov_b32_e32 v80, v0
	v_mov_b32_e32 v81, v0
	v_mov_b32_e32 v82, v0
	v_mov_b32_e32 v83, v0
	v_mov_b32_e32 v84, v0
	v_mov_b32_e32 v85, v0
	v_mov_b32_e32 v86, v0
	v_mov_b32_e32 v87, v0
	v_mov_b32_e32 v96, v0
	v_mov_b32_e32 v97, v0
	v_mov_b32_e32 v98, v0
	v_mov_b32_e32 v99, v0
	v_mov_b32_e32 v100, v0
	v_mov_b32_e32 v101, v0
	v_mov_b32_e32 v102, v0
	v_mov_b32_e32 v103, v0
	v_mov_b32_e32 v112, v0
	v_mov_b32_e32 v113, v0
	v_mov_b32_e32 v114, v0
	v_mov_b32_e32 v115, v0
	v_mov_b32_e32 v116, v0
	v_mov_b32_e32 v117, v0
	v_mov_b32_e32 v118, v0
	v_mov_b32_e32 v119, v0
	v_mov_b32_e32 v72, v0
	v_mov_b32_e32 v73, v0
	v_mov_b32_e32 v74, v0
	v_mov_b32_e32 v75, v0
	v_mov_b32_e32 v76, v0
	v_mov_b32_e32 v77, v0
	v_mov_b32_e32 v78, v0
	v_mov_b32_e32 v79, v0
	v_mov_b32_e32 v88, v0
	v_mov_b32_e32 v89, v0
	v_mov_b32_e32 v90, v0
	v_mov_b32_e32 v91, v0
	v_mov_b32_e32 v92, v0
	v_mov_b32_e32 v93, v0
	v_mov_b32_e32 v94, v0
	v_mov_b32_e32 v95, v0
	v_mov_b32_e32 v104, v0
	v_mov_b32_e32 v105, v0
	v_mov_b32_e32 v106, v0
	v_mov_b32_e32 v107, v0
	v_mov_b32_e32 v108, v0
	v_mov_b32_e32 v109, v0
	v_mov_b32_e32 v110, v0
	v_mov_b32_e32 v111, v0
	v_mov_b32_e32 v124, v0
	v_mov_b32_e32 v125, v0
	v_mov_b32_e32 v126, v0
	v_mov_b32_e32 v127, v0
	v_mov_b32_e32 v120, v0
	v_mov_b32_e32 v121, v0
	v_mov_b32_e32 v122, v0
	v_mov_b32_e32 v123, v0

.Lzinit_5:
	v_mov_b32_e32 v115, 0
	v_mov_b32_e32 v114, v115
	v_mov_b32_e32 v113, v115
	v_mov_b32_e32 v112, v115
	v_mov_b32_e32 v127, v115
	v_mov_b32_e32 v126, v115
	v_mov_b32_e32 v125, v115
	v_mov_b32_e32 v124, v115
	v_mov_b32_e32 v103, v115
	v_mov_b32_e32 v102, v115
	v_mov_b32_e32 v101, v115
	v_mov_b32_e32 v100, v115
	v_mov_b32_e32 v111, v115
	v_mov_b32_e32 v110, v115
	v_mov_b32_e32 v109, v115
	v_mov_b32_e32 v108, v115
	v_mov_b32_e32 v87, v115
	v_mov_b32_e32 v86, v115
	v_mov_b32_e32 v85, v115
	v_mov_b32_e32 v84, v115
	v_mov_b32_e32 v95, v115
	v_mov_b32_e32 v94, v115
	v_mov_b32_e32 v93, v115
	v_mov_b32_e32 v92, v115
	v_mov_b32_e32 v71, v115
	v_mov_b32_e32 v70, v115
	v_mov_b32_e32 v69, v115
	v_mov_b32_e32 v68, v115
	v_mov_b32_e32 v79, v115
	v_mov_b32_e32 v78, v115
	v_mov_b32_e32 v77, v115
	v_mov_b32_e32 v76, v115
	v_mov_b32_e32 v119, v115
	v_mov_b32_e32 v118, v115
	v_mov_b32_e32 v117, v115
	v_mov_b32_e32 v116, v115
	v_mov_b32_e32 v123, v115
	v_mov_b32_e32 v122, v115
	v_mov_b32_e32 v121, v115
	v_mov_b32_e32 v120, v115
	v_mov_b32_e32 v99, v115
	v_mov_b32_e32 v98, v115
	v_mov_b32_e32 v97, v115
	v_mov_b32_e32 v96, v115
	v_mov_b32_e32 v107, v115
	v_mov_b32_e32 v106, v115
	v_mov_b32_e32 v105, v115
	v_mov_b32_e32 v104, v115
	v_mov_b32_e32 v83, v115
	v_mov_b32_e32 v82, v115
	v_mov_b32_e32 v81, v115
	v_mov_b32_e32 v80, v115
	v_mov_b32_e32 v91, v115
	v_mov_b32_e32 v90, v115
	v_mov_b32_e32 v89, v115
	v_mov_b32_e32 v88, v115
	v_mov_b32_e32 v67, v115
	v_mov_b32_e32 v66, v115
	v_mov_b32_e32 v65, v115
	v_mov_b32_e32 v64, v115
	v_mov_b32_e32 v75, v115
	v_mov_b32_e32 v74, v115
	v_mov_b32_e32 v73, v115
	v_mov_b32_e32 v72, v115
	v_mov_b32_e32 v55, v115
	v_mov_b32_e32 v54, v115
	v_mov_b32_e32 v53, v115
	v_mov_b32_e32 v52, v115
	v_mov_b32_e32 v63, v115
	v_mov_b32_e32 v62, v115
	v_mov_b32_e32 v61, v115
	v_mov_b32_e32 v60, v115
	v_mov_b32_e32 v39, v115
	v_mov_b32_e32 v38, v115
	v_mov_b32_e32 v37, v115
	v_mov_b32_e32 v36, v115
	v_mov_b32_e32 v47, v115
	v_mov_b32_e32 v46, v115
	v_mov_b32_e32 v45, v115
	v_mov_b32_e32 v44, v115
	v_mov_b32_e32 v23, v115
	v_mov_b32_e32 v22, v115
	v_mov_b32_e32 v21, v115
	v_mov_b32_e32 v20, v115
	v_mov_b32_e32 v31, v115
	v_mov_b32_e32 v30, v115
	v_mov_b32_e32 v29, v115
	v_mov_b32_e32 v28, v115
	v_mov_b32_e32 v15, v115
	v_mov_b32_e32 v14, v115
	v_mov_b32_e32 v13, v115
	v_mov_b32_e32 v12, v115
	v_mov_b32_e32 v7, v115
	v_mov_b32_e32 v6, v115
	v_mov_b32_e32 v5, v115
	v_mov_b32_e32 v4, v115
	v_mov_b32_e32 v51, v115
	v_mov_b32_e32 v50, v115
	v_mov_b32_e32 v49, v115
	v_mov_b32_e32 v48, v115
	v_mov_b32_e32 v59, v115
	v_mov_b32_e32 v58, v115
	v_mov_b32_e32 v57, v115
	v_mov_b32_e32 v56, v115
	v_mov_b32_e32 v35, v115
	v_mov_b32_e32 v34, v115
	v_mov_b32_e32 v33, v115
	v_mov_b32_e32 v32, v115
	v_mov_b32_e32 v43, v115
	v_mov_b32_e32 v42, v115
	v_mov_b32_e32 v41, v115
	v_mov_b32_e32 v40, v115
	v_mov_b32_e32 v19, v115
	v_mov_b32_e32 v18, v115
	v_mov_b32_e32 v17, v115
	v_mov_b32_e32 v16, v115
	v_mov_b32_e32 v27, v115
	v_mov_b32_e32 v26, v115
	v_mov_b32_e32 v25, v115
	v_mov_b32_e32 v24, v115
	v_mov_b32_e32 v11, v115
	v_mov_b32_e32 v10, v115
	v_mov_b32_e32 v9, v115
	v_mov_b32_e32 v8, v115
	v_mov_b32_e32 v3, v115
	v_mov_b32_e32 v2, v115
	v_mov_b32_e32 v1, v115
	v_mov_b32_e32 v0, v115
	s_branch .LBB0_1757

.LBB0_1754:
	s_andn2_b64 vcc, exec, s[26:27]
	s_cbranch_vccnz .Lzinit_5
	s_add_u32 s40, s42, 0x80
	s_addc_u32 s41, s43, 0
	s_add_u32 s33, s28, 0x100
	v_mov_b32_e32 v0, 0
	s_addc_u32 s42, s29, 0
	s_mov_b32 s28, 0
	v_mov_b32_e32 v1, v0
	v_mov_b32_e32 v2, v0
	v_mov_b32_e32 v3, v0
	v_mov_b32_e32 v8, v0
	v_mov_b32_e32 v9, v0
	v_mov_b32_e32 v10, v0
	v_mov_b32_e32 v11, v0
	v_mov_b32_e32 v24, v0
	v_mov_b32_e32 v25, v0
	v_mov_b32_e32 v26, v0
	v_mov_b32_e32 v27, v0
	v_mov_b32_e32 v16, v0
	v_mov_b32_e32 v17, v0
	v_mov_b32_e32 v18, v0
	v_mov_b32_e32 v19, v0
	v_mov_b32_e32 v40, v0
	v_mov_b32_e32 v41, v0
	v_mov_b32_e32 v42, v0
	v_mov_b32_e32 v43, v0
	v_mov_b32_e32 v32, v0
	v_mov_b32_e32 v33, v0
	v_mov_b32_e32 v34, v0
	v_mov_b32_e32 v35, v0
	v_mov_b32_e32 v56, v0
	v_mov_b32_e32 v57, v0
	v_mov_b32_e32 v58, v0
	v_mov_b32_e32 v59, v0
	v_mov_b32_e32 v48, v0
	v_mov_b32_e32 v49, v0
	v_mov_b32_e32 v50, v0
	v_mov_b32_e32 v51, v0
	v_mov_b32_e32 v4, v0
	v_mov_b32_e32 v5, v0
	v_mov_b32_e32 v6, v0
	v_mov_b32_e32 v7, v0
	v_mov_b32_e32 v12, v0
	v_mov_b32_e32 v13, v0
	v_mov_b32_e32 v14, v0
	v_mov_b32_e32 v15, v0
	v_mov_b32_e32 v28, v0
	v_mov_b32_e32 v29, v0
	v_mov_b32_e32 v30, v0
	v_mov_b32_e32 v31, v0
	v_mov_b32_e32 v20, v0
	v_mov_b32_e32 v21, v0
	v_mov_b32_e32 v22, v0
	v_mov_b32_e32 v23, v0
	v_mov_b32_e32 v44, v0
	v_mov_b32_e32 v45, v0
	v_mov_b32_e32 v46, v0
	v_mov_b32_e32 v47, v0
	v_mov_b32_e32 v36, v0
	v_mov_b32_e32 v37, v0
	v_mov_b32_e32 v38, v0
	v_mov_b32_e32 v39, v0
	v_mov_b32_e32 v60, v0
	v_mov_b32_e32 v61, v0
	v_mov_b32_e32 v62, v0
	v_mov_b32_e32 v63, v0
	v_mov_b32_e32 v52, v0
	v_mov_b32_e32 v53, v0
	v_mov_b32_e32 v54, v0
	v_mov_b32_e32 v55, v0
	v_mov_b32_e32 v72, v0
	v_mov_b32_e32 v73, v0
	v_mov_b32_e32 v74, v0
	v_mov_b32_e32 v75, v0
	v_mov_b32_e32 v64, v0
	v_mov_b32_e32 v65, v0
	v_mov_b32_e32 v66, v0
	v_mov_b32_e32 v67, v0
	v_mov_b32_e32 v88, v0
	v_mov_b32_e32 v89, v0
	v_mov_b32_e32 v90, v0
	v_mov_b32_e32 v91, v0
	v_mov_b32_e32 v80, v0
	v_mov_b32_e32 v81, v0
	v_mov_b32_e32 v82, v0
	v_mov_b32_e32 v83, v0
	v_mov_b32_e32 v104, v0
	v_mov_b32_e32 v105, v0
	v_mov_b32_e32 v106, v0
	v_mov_b32_e32 v107, v0
	v_mov_b32_e32 v96, v0
	v_mov_b32_e32 v97, v0
	v_mov_b32_e32 v98, v0
	v_mov_b32_e32 v99, v0
	v_mov_b32_e32 v120, v0
	v_mov_b32_e32 v121, v0
	v_mov_b32_e32 v122, v0
	v_mov_b32_e32 v123, v0
	v_mov_b32_e32 v116, v0
	v_mov_b32_e32 v117, v0
	v_mov_b32_e32 v118, v0
	v_mov_b32_e32 v119, v0
	v_mov_b32_e32 v76, v0
	v_mov_b32_e32 v77, v0
	v_mov_b32_e32 v78, v0
	v_mov_b32_e32 v79, v0
	v_mov_b32_e32 v68, v0
	v_mov_b32_e32 v69, v0
	v_mov_b32_e32 v70, v0
	v_mov_b32_e32 v71, v0
	v_mov_b32_e32 v92, v0
	v_mov_b32_e32 v93, v0
	v_mov_b32_e32 v94, v0
	v_mov_b32_e32 v95, v0
	v_mov_b32_e32 v84, v0
	v_mov_b32_e32 v85, v0
	v_mov_b32_e32 v86, v0
	v_mov_b32_e32 v87, v0
	v_mov_b32_e32 v108, v0
	v_mov_b32_e32 v109, v0
	v_mov_b32_e32 v110, v0
	v_mov_b32_e32 v111, v0
	v_mov_b32_e32 v100, v0
	v_mov_b32_e32 v101, v0
	v_mov_b32_e32 v102, v0
	v_mov_b32_e32 v103, v0
	v_mov_b32_e32 v124, v0
	v_mov_b32_e32 v125, v0
	v_mov_b32_e32 v126, v0
	v_mov_b32_e32 v127, v0
	v_mov_b32_e32 v112, v0
	v_mov_b32_e32 v113, v0
	v_mov_b32_e32 v114, v0
	v_mov_b32_e32 v115, v0

.Lzinit_7:
	v_mov_b32_e32 v127, 0
	v_mov_b32_e32 v126, v127
	v_mov_b32_e32 v125, v127
	v_mov_b32_e32 v124, v127
	v_mov_b32_e32 v123, v127
	v_mov_b32_e32 v122, v127
	v_mov_b32_e32 v121, v127
	v_mov_b32_e32 v120, v127
	v_mov_b32_e32 v111, v127
	v_mov_b32_e32 v110, v127
	v_mov_b32_e32 v109, v127
	v_mov_b32_e32 v108, v127
	v_mov_b32_e32 v107, v127
	v_mov_b32_e32 v106, v127
	v_mov_b32_e32 v105, v127
	v_mov_b32_e32 v104, v127
	v_mov_b32_e32 v95, v127
	v_mov_b32_e32 v94, v127
	v_mov_b32_e32 v93, v127
	v_mov_b32_e32 v92, v127
	v_mov_b32_e32 v91, v127
	v_mov_b32_e32 v90, v127
	v_mov_b32_e32 v89, v127
	v_mov_b32_e32 v88, v127
	v_mov_b32_e32 v79, v127
	v_mov_b32_e32 v78, v127
	v_mov_b32_e32 v77, v127
	v_mov_b32_e32 v76, v127
	v_mov_b32_e32 v75, v127
	v_mov_b32_e32 v74, v127
	v_mov_b32_e32 v73, v127
	v_mov_b32_e32 v72, v127
	v_mov_b32_e32 v119, v127
	v_mov_b32_e32 v118, v127
	v_mov_b32_e32 v117, v127
	v_mov_b32_e32 v116, v127
	v_mov_b32_e32 v115, v127
	v_mov_b32_e32 v114, v127
	v_mov_b32_e32 v113, v127
	v_mov_b32_e32 v112, v127
	v_mov_b32_e32 v103, v127
	v_mov_b32_e32 v102, v127
	v_mov_b32_e32 v101, v127
	v_mov_b32_e32 v100, v127
	v_mov_b32_e32 v99, v127
	v_mov_b32_e32 v98, v127
	v_mov_b32_e32 v97, v127
	v_mov_b32_e32 v96, v127
	v_mov_b32_e32 v87, v127
	v_mov_b32_e32 v86, v127
	v_mov_b32_e32 v85, v127
	v_mov_b32_e32 v84, v127
	v_mov_b32_e32 v83, v127
	v_mov_b32_e32 v82, v127
	v_mov_b32_e32 v81, v127
	v_mov_b32_e32 v80, v127
	v_mov_b32_e32 v71, v127
	v_mov_b32_e32 v70, v127
	v_mov_b32_e32 v69, v127
	v_mov_b32_e32 v68, v127
	v_mov_b32_e32 v67, v127
	v_mov_b32_e32 v66, v127
	v_mov_b32_e32 v65, v127
	v_mov_b32_e32 v64, v127
	v_mov_b32_e32 v63, v127
	v_mov_b32_e32 v62, v127
	v_mov_b32_e32 v61, v127
	v_mov_b32_e32 v60, v127
	v_mov_b32_e32 v59, v127
	v_mov_b32_e32 v58, v127
	v_mov_b32_e32 v57, v127
	v_mov_b32_e32 v56, v127
	v_mov_b32_e32 v47, v127
	v_mov_b32_e32 v46, v127
	v_mov_b32_e32 v45, v127
	v_mov_b32_e32 v44, v127
	v_mov_b32_e32 v43, v127
	v_mov_b32_e32 v42, v127
	v_mov_b32_e32 v41, v127
	v_mov_b32_e32 v40, v127
	v_mov_b32_e32 v31, v127
	v_mov_b32_e32 v30, v127
	v_mov_b32_e32 v29, v127
	v_mov_b32_e32 v28, v127
	v_mov_b32_e32 v27, v127
	v_mov_b32_e32 v26, v127
	v_mov_b32_e32 v25, v127
	v_mov_b32_e32 v24, v127
	v_mov_b32_e32 v15, v127
	v_mov_b32_e32 v14, v127
	v_mov_b32_e32 v13, v127
	v_mov_b32_e32 v12, v127
	v_mov_b32_e32 v11, v127
	v_mov_b32_e32 v10, v127
	v_mov_b32_e32 v9, v127
	v_mov_b32_e32 v8, v127
	v_mov_b32_e32 v55, v127
	v_mov_b32_e32 v54, v127
	v_mov_b32_e32 v53, v127
	v_mov_b32_e32 v52, v127
	v_mov_b32_e32 v51, v127
	v_mov_b32_e32 v50, v127
	v_mov_b32_e32 v49, v127
	v_mov_b32_e32 v48, v127
	v_mov_b32_e32 v39, v127
	v_mov_b32_e32 v38, v127
	v_mov_b32_e32 v37, v127
	v_mov_b32_e32 v36, v127
	v_mov_b32_e32 v35, v127
	v_mov_b32_e32 v34, v127
	v_mov_b32_e32 v33, v127
	v_mov_b32_e32 v32, v127
	v_mov_b32_e32 v23, v127
	v_mov_b32_e32 v22, v127
	v_mov_b32_e32 v21, v127
	v_mov_b32_e32 v20, v127
	v_mov_b32_e32 v19, v127
	v_mov_b32_e32 v18, v127
	v_mov_b32_e32 v17, v127
	v_mov_b32_e32 v16, v127
	v_mov_b32_e32 v7, v127
	v_mov_b32_e32 v6, v127
	v_mov_b32_e32 v5, v127
	v_mov_b32_e32 v4, v127
	v_mov_b32_e32 v3, v127
	v_mov_b32_e32 v2, v127
	v_mov_b32_e32 v1, v127
	v_mov_b32_e32 v0, v127
	s_branch .LBB0_2320

.LBB0_2317:
	s_andn2_b64 vcc, exec, s[36:37]
	s_cbranch_vccnz .Lzinit_7
	s_add_u32 s46, s46, 0x80
	s_addc_u32 s47, s47, 0
	s_add_u32 s33, s28, 0x100
	v_mov_b32_e32 v0, 0
	s_addc_u32 s63, s29, 0
	s_mov_b32 s28, 0
	v_mov_b32_e32 v1, v0
	v_mov_b32_e32 v2, v0
	v_mov_b32_e32 v3, v0
	v_mov_b32_e32 v4, v0
	v_mov_b32_e32 v5, v0
	v_mov_b32_e32 v6, v0
	v_mov_b32_e32 v7, v0
	v_mov_b32_e32 v16, v0
	v_mov_b32_e32 v17, v0
	v_mov_b32_e32 v18, v0
	v_mov_b32_e32 v19, v0
	v_mov_b32_e32 v20, v0
	v_mov_b32_e32 v21, v0
	v_mov_b32_e32 v22, v0
	v_mov_b32_e32 v23, v0
	v_mov_b32_e32 v32, v0
	v_mov_b32_e32 v33, v0
	v_mov_b32_e32 v34, v0
	v_mov_b32_e32 v35, v0
	v_mov_b32_e32 v36, v0
	v_mov_b32_e32 v37, v0
	v_mov_b32_e32 v38, v0
	v_mov_b32_e32 v39, v0
	v_mov_b32_e32 v48, v0
	v_mov_b32_e32 v49, v0
	v_mov_b32_e32 v50, v0
	v_mov_b32_e32 v51, v0
	v_mov_b32_e32 v52, v0
	v_mov_b32_e32 v53, v0
	v_mov_b32_e32 v54, v0
	v_mov_b32_e32 v55, v0
	v_mov_b32_e32 v8, v0
	v_mov_b32_e32 v9, v0
	v_mov_b32_e32 v10, v0
	v_mov_b32_e32 v11, v0
	v_mov_b32_e32 v12, v0
	v_mov_b32_e32 v13, v0
	v_mov_b32_e32 v14, v0
	v_mov_b32_e32 v15, v0
	v_mov_b32_e32 v24, v0
	v_mov_b32_e32 v25, v0
	v_mov_b32_e32 v26, v0
	v_mov_b32_e32 v27, v0
	v_mov_b32_e32 v28, v0
	v_mov_b32_e32 v29, v0
	v_mov_b32_e32 v30, v0
	v_mov_b32_e32 v31, v0
	v_mov_b32_e32 v40, v0
	v_mov_b32_e32 v41, v0
	v_mov_b32_e32 v42, v0
	v_mov_b32_e32 v43, v0
	v_mov_b32_e32 v44, v0
	v_mov_b32_e32 v45, v0
	v_mov_b32_e32 v46, v0
	v_mov_b32_e32 v47, v0
	v_mov_b32_e32 v56, v0
	v_mov_b32_e32 v57, v0
	v_mov_b32_e32 v58, v0
	v_mov_b32_e32 v59, v0
	v_mov_b32_e32 v60, v0
	v_mov_b32_e32 v61, v0
	v_mov_b32_e32 v62, v0
	v_mov_b32_e32 v63, v0
	v_mov_b32_e32 v64, v0
	v_mov_b32_e32 v65, v0
	v_mov_b32_e32 v66, v0
	v_mov_b32_e32 v67, v0
	v_mov_b32_e32 v68, v0
	v_mov_b32_e32 v69, v0
	v_mov_b32_e32 v70, v0
	v_mov_b32_e32 v71, v0
	v_mov_b32_e32 v80, v0
	v_mov_b32_e32 v81, v0
	v_mov_b32_e32 v82, v0
	v_mov_b32_e32 v83, v0
	v_mov_b32_e32 v84, v0
	v_mov_b32_e32 v85, v0
	v_mov_b32_e32 v86, v0
	v_mov_b32_e32 v87, v0
	v_mov_b32_e32 v96, v0
	v_mov_b32_e32 v97, v0
	v_mov_b32_e32 v98, v0
	v_mov_b32_e32 v99, v0
	v_mov_b32_e32 v100, v0
	v_mov_b32_e32 v101, v0
	v_mov_b32_e32 v102, v0
	v_mov_b32_e32 v103, v0
	v_mov_b32_e32 v112, v0
	v_mov_b32_e32 v113, v0
	v_mov_b32_e32 v114, v0
	v_mov_b32_e32 v115, v0
	v_mov_b32_e32 v116, v0
	v_mov_b32_e32 v117, v0
	v_mov_b32_e32 v118, v0
	v_mov_b32_e32 v119, v0
	v_mov_b32_e32 v72, v0
	v_mov_b32_e32 v73, v0
	v_mov_b32_e32 v74, v0
	v_mov_b32_e32 v75, v0
	v_mov_b32_e32 v76, v0
	v_mov_b32_e32 v77, v0
	v_mov_b32_e32 v78, v0
	v_mov_b32_e32 v79, v0
	v_mov_b32_e32 v88, v0
	v_mov_b32_e32 v89, v0
	v_mov_b32_e32 v90, v0
	v_mov_b32_e32 v91, v0
	v_mov_b32_e32 v92, v0
	v_mov_b32_e32 v93, v0
	v_mov_b32_e32 v94, v0
	v_mov_b32_e32 v95, v0
	v_mov_b32_e32 v104, v0
	v_mov_b32_e32 v105, v0
	v_mov_b32_e32 v106, v0
	v_mov_b32_e32 v107, v0
	v_mov_b32_e32 v108, v0
	v_mov_b32_e32 v109, v0
	v_mov_b32_e32 v110, v0
	v_mov_b32_e32 v111, v0
	v_mov_b32_e32 v120, v0
	v_mov_b32_e32 v121, v0
	v_mov_b32_e32 v122, v0
	v_mov_b32_e32 v123, v0
	v_mov_b32_e32 v124, v0
	v_mov_b32_e32 v125, v0
	v_mov_b32_e32 v126, v0
	v_mov_b32_e32 v127, v0
